# v12 (v11 + SGPR-base LDS-DMA loads in the down and in-proj GEMM loops) + gate/up K-loop: pointer selection rotated to the end of the previous iteration, LDS reads issued first after each barrier with
# baseline (speedup 1.0000x reference)
; #define PG8_STAGE(bufoff, gbase, voff) do { _Pragma("unroll") for (int _i = 0; _i < 2; ++_i) \
;         __builtin_amdgcn_global_load_lds((const unsigned*)((const char*)(gbase) + (voff)[_i]), (PG8_LAS unsigned*)(lds + (bufoff) + ldsw + _i * 8192), 16, 0, 0); } while (0)
; #define PG8_LDA(dst, b, h) do { _Pragma("unroll") for (int m = 0; m < 4; ++m) _Pragma("unroll") for (int k = 0; k < 2; ++k) dst[m][k] = *(const PG8_LAS bf16x8*)(lds + PG8_SA(b, h) + aoff + m * 2048 + k * 1024); } while (0)
; #define PG8_LDB(dst, b, h) do { _Pragma("unroll") for (int n = 0; n < 2; ++n) _Pragma("unroll") for (int k = 0; k < 2; ++k) dst[n][k] = *(const PG8_LAS bf16x8*)(lds + PG8_SB(b, h) + boff + n * 2048 + k * 1024); } while (0)
; #define PG8_MMA(ai, bj, At, Bt) do { __builtin_amdgcn_s_setprio(1); _Pragma("unroll") for (int m = 0; m < 4; ++m) _Pragma("unroll") for (int n = 0; n < 2; ++n) _Pragma("unroll") for (int k = 0; k < 2; ++k) \
;         acc[ai][bj][m][n] = __builtin_amdgcn_mfma_f32_16x16x32_bf16(Bt[n][k], At[m][k], acc[ai][bj][m][n], 0, 0, 0); __builtin_amdgcn_s_setprio(0); } while (0)
; #define PG8_BAR __builtin_amdgcn_s_barrier()
; template <class Epi, class Sched, bool ALIGN_EPI = false, bool SP2 = false>
; __device__ __forceinline__ void gemm_phase(PG8_LAS unsigned char* lds, const Gemm g, const Sched& S, const Epi& E) {
;     ...
;             const bool last = (t == nt - 2);
;             const char* a1 = cA + (size_t)(t + 1) * kstep;
;             const char* a2 = last ? nA : cA + (size_t)(t + 2) * kstep; const char* b2 = last ? nB : cB + (size_t)(t + 2) * kstep;
;             const char* a3 = a2 + kstep; const char* b3 = b2 + kstep;
;             if (last && has_next) S.a_ready(nxt);
;             if constexpr (SP2) {
;             PG8_LDB(B0, 0, 0); PG8_LDB(B1, 0, 1); PG8_SCHED; PG8_LDA(At, 0, 0); PG8_STAGE(PG8_SA(1, 1), a1 + hstep, voffA);
;             PG8_WAIT_V(8); PG8_WAIT_L(0); PG8_BAR; PG8_MMA(0, 0, At, B0); PG8_MMA(0, 1, At, B1); PG8_BAR; PG8_SCHED;
;             PG8_LDA(At, 0, 1); PG8_STAGE(PG8_SB(0, 0), b2, voffB); PG8_STAGE(PG8_SB(0, 1), b2 + hstep, voffB); PG8_STAGE(PG8_SA(0, 0), a2, voffA);
;             PG8_WAIT_V(8); PG8_WAIT_L(0); PG8_BAR; PG8_MMA(1, 0, At, B0); PG8_MMA(1, 1, At, B1); PG8_BAR; PG8_SCHED;
;             PG8_LDB(B0, 1, 0); PG8_LDB(B1, 1, 1); PG8_SCHED; PG8_LDA(At, 1, 0); PG8_STAGE(PG8_SA(0, 1), a2 + hstep, voffA);
.LBB0_492:
	s_ashr_i32 s17, s16, 31
	s_lshl_b64 s[18:19], s[16:17], 19
	s_add_u32 s18, s94, s18
	s_addc_u32 s19, s95, s19
	s_and_b64 s[20:21], s[4:5], exec
	s_cselect_b32 s17, s19, s23
	s_cselect_b32 s46, s18, s22
	s_ashr_i32 s15, s14, 31
	s_lshl_b64 s[20:21], s[14:15], 19
	s_add_u32 s20, s28, s20
	s_addc_u32 s21, s29, s21
	s_and_b64 s[26:27], s[4:5], exec
	s_cselect_b32 s15, s21, s25
	s_cselect_b32 s47, s20, s24
	s_add_u32 s22, s22, 0x40080
	s_addc_u32 s23, s23, 0
	s_add_u32 s48, s24, 0x100
	s_addc_u32 s49, s25, 0
	s_mov_b32 s50, -2
	v_add_u32_e32 v146, 0x10000, v149
	v_add_u32_e32 v147, 0x14000, v149
	v_add_u32_e32 v156, 0x18000, v149
	v_add_u32_e32 v157, 0x1c000, v149
	s_add_u32 s24, s22, 0xfffc0080
	s_addc_u32 s25, s23, -1
	s_add_i32 s51, 0, 0x10000
	s_cmp_eq_u32 s50, 12
	s_cselect_b32 s27, s17, s25
	s_cselect_b32 s26, s46, s24
	s_cselect_b32 s25, s15, s49
	s_cselect_b32 s24, s47, s48
	s_add_i32 s54, 0, 0x14000
	ds_read_b128 v[142:145], v146
	ds_read_b128 v[152:155], v146 offset:1024
	ds_read_b128 v[172:175], v146 offset:2048
	ds_read_b128 v[176:179], v146 offset:3072
	ds_read_b128 v[180:183], v147
	ds_read_b128 v[184:187], v147 offset:1024
	ds_read_b128 v[188:191], v147 offset:2048
	ds_read_b128 v[192:195], v147 offset:3072
	s_add_i32 m0, s30, 0xc000
	ds_read_b128 v[196:199], v151
	ds_read_b128 v[214:217], v151 offset:1024
	ds_read_b128 v[218:221], v151 offset:2048
	ds_read_b128 v[222:225], v151 offset:3072
	ds_read_b128 v[226:229], v151 offset:4096
	ds_read_b128 v[230:233], v151 offset:5120
	ds_read_b128 v[234:237], v151 offset:6144
	ds_read_b128 v[238:241], v151 offset:7168
	global_load_lds_dwordx4 v138, s[22:23]
	s_add_i32 m0, s30, 0xe000
	s_nop 0
	global_load_lds_dwordx4 v140, s[22:23]
	s_waitcnt vmcnt(8)
	s_waitcnt lgkmcnt(0)
	s_barrier
	s_setprio 1
	s_waitcnt lgkmcnt(0)
	v_mfma_f32_16x16x32_bf16 v[126:129], v[142:145], v[196:199], 0
	v_mfma_f32_16x16x32_bf16 v[118:121], v[172:175], v[196:199], 0
	v_mfma_f32_16x16x32_bf16 v[110:113], v[142:145], v[218:221], 0
	v_mfma_f32_16x16x32_bf16 v[102:105], v[172:175], v[218:221], 0
	v_mfma_f32_16x16x32_bf16 v[94:97], v[142:145], v[226:229], 0
	v_mfma_f32_16x16x32_bf16 v[86:89], v[172:175], v[226:229], 0
	v_mfma_f32_16x16x32_bf16 v[78:81], v[142:145], v[234:237], 0
	v_mfma_f32_16x16x32_bf16 v[70:73], v[172:175], v[234:237], 0
	v_mfma_f32_16x16x32_bf16 v[126:129], v[152:155], v[214:217], v[126:129]
	v_mfma_f32_16x16x32_bf16 v[118:121], v[176:179], v[214:217], v[118:121]
	v_mfma_f32_16x16x32_bf16 v[110:113], v[152:155], v[222:225], v[110:113]
	v_mfma_f32_16x16x32_bf16 v[102:105], v[176:179], v[222:225], v[102:105]
	v_mfma_f32_16x16x32_bf16 v[94:97], v[152:155], v[230:233], v[94:97]
	v_mfma_f32_16x16x32_bf16 v[86:89], v[176:179], v[230:233], v[86:89]
	v_mfma_f32_16x16x32_bf16 v[78:81], v[152:155], v[238:241], v[78:81]
	v_mfma_f32_16x16x32_bf16 v[70:73], v[176:179], v[238:241], v[70:73]
	s_setprio 0
	s_setprio 1
	v_mfma_f32_16x16x32_bf16 v[122:125], v[180:183], v[196:199], 0
	v_mfma_f32_16x16x32_bf16 v[114:117], v[188:191], v[196:199], 0
	v_mfma_f32_16x16x32_bf16 v[106:109], v[180:183], v[218:221], 0
	v_mfma_f32_16x16x32_bf16 v[98:101], v[188:191], v[218:221], 0
	v_mfma_f32_16x16x32_bf16 v[90:93], v[180:183], v[226:229], 0
	v_mfma_f32_16x16x32_bf16 v[82:85], v[188:191], v[226:229], 0
	v_mfma_f32_16x16x32_bf16 v[74:77], v[180:183], v[234:237], 0
	v_mfma_f32_16x16x32_bf16 v[66:69], v[188:191], v[234:237], 0
	v_mfma_f32_16x16x32_bf16 v[122:125], v[184:187], v[214:217], v[122:125]
	v_mfma_f32_16x16x32_bf16 v[114:117], v[192:195], v[214:217], v[114:117]
	v_mfma_f32_16x16x32_bf16 v[106:109], v[184:187], v[222:225], v[106:109]
	v_mfma_f32_16x16x32_bf16 v[98:101], v[192:195], v[222:225], v[98:101]
	v_mfma_f32_16x16x32_bf16 v[90:93], v[184:187], v[230:233], v[90:93]
	v_mfma_f32_16x16x32_bf16 v[82:85], v[192:195], v[230:233], v[82:85]
	v_mfma_f32_16x16x32_bf16 v[74:77], v[184:187], v[238:241], v[74:77]
	v_mfma_f32_16x16x32_bf16 v[66:69], v[192:195], v[238:241], v[66:69]
	s_setprio 0
	s_barrier
	ds_read_b128 v[196:199], v151 offset:16384
	ds_read_b128 v[214:217], v151 offset:17408
	ds_read_b128 v[218:221], v151 offset:18432
	ds_read_b128 v[222:225], v151 offset:19456
	s_add_i32 s51, s51, s2
	s_mov_b32 m0, s51
	ds_read_b128 v[226:229], v151 offset:20480
	ds_read_b128 v[230:233], v151 offset:21504
	ds_read_b128 v[234:237], v151 offset:22528
	ds_read_b128 v[238:241], v151 offset:23552
	global_load_lds_dwordx4 v0, s[24:25]
	s_add_i32 m0, s51, 0x2000
	s_add_u32 s52, s24, 0x40000
	s_addc_u32 s53, s25, 0
	s_add_i32 s51, s54, s2
	global_load_lds_dwordx4 v130, s[24:25]
	s_mov_b32 m0, s51
	s_nop 0
	global_load_lds_dwordx4 v0, s[52:53]
	s_add_i32 m0, s51, 0x2000
	s_nop 0
	global_load_lds_dwordx4 v130, s[52:53]
	s_mov_b32 m0, s30
	s_nop 0
	global_load_lds_dwordx4 v134, s[26:27]
	s_mov_b32 m0, s31
	s_nop 0
	global_load_lds_dwordx4 v132, s[26:27]
	s_waitcnt vmcnt(8)
	s_waitcnt lgkmcnt(0)
	s_barrier
; #define PG8_STAGE(bufoff, gbase, voff) do { _Pragma("unroll") for (int _i = 0; _i < 2; ++_i) \
;         __builtin_amdgcn_global_load_lds((const unsigned*)((const char*)(gbase) + (voff)[_i]), (PG8_LAS unsigned*)(lds + (bufoff) + ldsw + _i * 8192), 16, 0, 0); } while (0)
; #define PG8_LDA(dst, b, h) do { _Pragma("unroll") for (int m = 0; m < 4; ++m) _Pragma("unroll") for (int k = 0; k < 2; ++k) dst[m][k] = *(const PG8_LAS bf16x8*)(lds + PG8_SA(b, h) + aoff + m * 2048 + k * 1024); } while (0)
; #define PG8_LDB(dst, b, h) do { _Pragma("unroll") for (int n = 0; n < 2; ++n) _Pragma("unroll") for (int k = 0; k < 2; ++k) dst[n][k] = *(const PG8_LAS bf16x8*)(lds + PG8_SB(b, h) + boff + n * 2048 + k * 1024); } while (0)
; #define PG8_MMA(ai, bj, At, Bt) do { __builtin_amdgcn_s_setprio(1); _Pragma("unroll") for (int m = 0; m < 4; ++m) _Pragma("unroll") for (int n = 0; n < 2; ++n) _Pragma("unroll") for (int k = 0; k < 2; ++k) \
;         acc[ai][bj][m][n] = __builtin_amdgcn_mfma_f32_16x16x32_bf16(Bt[n][k], At[m][k], acc[ai][bj][m][n], 0, 0, 0); __builtin_amdgcn_s_setprio(0); } while (0)
; #define PG8_WAIT_V(n) asm volatile("s_waitcnt vmcnt(" #n ")" ::: "memory")
; #define PG8_WAIT_L(n) asm volatile("s_waitcnt lgkmcnt(" #n ")" ::: "memory")
; #define PG8_BAR __builtin_amdgcn_s_barrier()
; #define PG8_SCHED __builtin_amdgcn_sched_barrier(0)
; template <class Epi, class Sched, bool ALIGN_EPI = false, bool SP2 = false>
; __device__ __forceinline__ void gemm_phase(PG8_LAS unsigned char* lds, const Gemm g, const Sched& S, const Epi& E) {
;     ...
;             PG8_LDA(At, 0, 1); PG8_STAGE(PG8_SB(0, 0), b2, voffB); PG8_STAGE(PG8_SB(0, 1), b2 + hstep, voffB); PG8_STAGE(PG8_SA(0, 0), a2, voffA);
;             PG8_WAIT_V(8); PG8_WAIT_L(0); PG8_BAR; PG8_MMA(1, 0, At, B0); PG8_MMA(1, 1, At, B1); PG8_BAR; PG8_SCHED;
;             PG8_LDB(B0, 1, 0); PG8_LDB(B1, 1, 1); PG8_SCHED; PG8_LDA(At, 1, 0); PG8_STAGE(PG8_SA(0, 1), a2 + hstep, voffA);
;             PG8_WAIT_V(8); PG8_WAIT_L(0); PG8_BAR; PG8_MMA(0, 0, At, B0); PG8_MMA(0, 1, At, B1); PG8_BAR; PG8_SCHED;
;             PG8_LDA(At, 1, 1); PG8_STAGE(PG8_SB(1, 0), b3, voffB); PG8_STAGE(PG8_SB(1, 1), b3 + hstep, voffB); PG8_STAGE(PG8_SA(1, 0), a3, voffA);
	s_setprio 1
	s_waitcnt lgkmcnt(0)
	v_mfma_f32_16x16x32_bf16 v[62:65], v[142:145], v[196:199], 0
	v_mfma_f32_16x16x32_bf16 v[54:57], v[172:175], v[196:199], 0
	v_mfma_f32_16x16x32_bf16 v[46:49], v[142:145], v[218:221], 0
	v_mfma_f32_16x16x32_bf16 v[38:41], v[172:175], v[218:221], 0
	v_mfma_f32_16x16x32_bf16 v[30:33], v[142:145], v[226:229], 0
	v_mfma_f32_16x16x32_bf16 v[22:25], v[172:175], v[226:229], 0
	v_mfma_f32_16x16x32_bf16 v[14:17], v[142:145], v[234:237], 0
	v_mfma_f32_16x16x32_bf16 v[6:9], v[172:175], v[234:237], 0
	v_mfma_f32_16x16x32_bf16 v[62:65], v[152:155], v[214:217], v[62:65]
	v_mfma_f32_16x16x32_bf16 v[54:57], v[176:179], v[214:217], v[54:57]
	v_mfma_f32_16x16x32_bf16 v[46:49], v[152:155], v[222:225], v[46:49]
	v_mfma_f32_16x16x32_bf16 v[38:41], v[176:179], v[222:225], v[38:41]
	v_mfma_f32_16x16x32_bf16 v[30:33], v[152:155], v[230:233], v[30:33]
	v_mfma_f32_16x16x32_bf16 v[22:25], v[176:179], v[230:233], v[22:25]
	v_mfma_f32_16x16x32_bf16 v[14:17], v[152:155], v[238:241], v[14:17]
	v_mfma_f32_16x16x32_bf16 v[6:9], v[176:179], v[238:241], v[6:9]
	s_setprio 0
	s_setprio 1
	v_mfma_f32_16x16x32_bf16 v[58:61], v[180:183], v[196:199], 0
	v_mfma_f32_16x16x32_bf16 v[50:53], v[188:191], v[196:199], 0
	v_mfma_f32_16x16x32_bf16 v[42:45], v[180:183], v[218:221], 0
	v_mfma_f32_16x16x32_bf16 v[34:37], v[188:191], v[218:221], 0
	v_mfma_f32_16x16x32_bf16 v[26:29], v[180:183], v[226:229], 0
	v_mfma_f32_16x16x32_bf16 v[18:21], v[188:191], v[226:229], 0
	v_mfma_f32_16x16x32_bf16 v[10:13], v[180:183], v[234:237], 0
	v_mfma_f32_16x16x32_bf16 v[2:5], v[188:191], v[234:237], 0
	v_mfma_f32_16x16x32_bf16 v[58:61], v[184:187], v[214:217], v[58:61]
	v_mfma_f32_16x16x32_bf16 v[50:53], v[192:195], v[214:217], v[50:53]
	v_mfma_f32_16x16x32_bf16 v[42:45], v[184:187], v[222:225], v[42:45]
	v_mfma_f32_16x16x32_bf16 v[34:37], v[192:195], v[222:225], v[34:37]
	v_mfma_f32_16x16x32_bf16 v[26:29], v[184:187], v[230:233], v[26:29]
	v_mfma_f32_16x16x32_bf16 v[18:21], v[192:195], v[230:233], v[18:21]
	v_mfma_f32_16x16x32_bf16 v[10:13], v[184:187], v[238:241], v[10:13]
	v_mfma_f32_16x16x32_bf16 v[2:5], v[192:195], v[238:241], v[2:5]
	s_setprio 0
	s_barrier
	ds_read_b128 v[142:145], v156
	ds_read_b128 v[152:155], v156 offset:1024
	ds_read_b128 v[172:175], v156 offset:2048
	ds_read_b128 v[176:179], v156 offset:3072
	ds_read_b128 v[180:183], v157
	ds_read_b128 v[184:187], v157 offset:1024
	ds_read_b128 v[188:191], v157 offset:2048
	ds_read_b128 v[192:195], v157 offset:3072
	s_add_i32 s51, 0, 0x18000
	s_add_i32 s52, 0, 0x1c000
	s_add_u32 s26, s26, 0x40000
	s_addc_u32 s27, s27, 0
	s_mov_b32 m0, s34
	ds_read_b128 v[196:199], v151 offset:32768
	ds_read_b128 v[214:217], v151 offset:33792
	ds_read_b128 v[218:221], v151 offset:34816
	ds_read_b128 v[222:225], v151 offset:35840
	ds_read_b128 v[226:229], v151 offset:36864
	ds_read_b128 v[230:233], v151 offset:37888
	ds_read_b128 v[234:237], v151 offset:38912
	ds_read_b128 v[238:241], v151 offset:39936
	global_load_lds_dwordx4 v134, s[26:27]
	s_mov_b32 m0, s35
	s_nop 0
	global_load_lds_dwordx4 v132, s[26:27]
	s_waitcnt vmcnt(8)
	s_waitcnt lgkmcnt(0)
	s_barrier
	s_setprio 1
	s_waitcnt lgkmcnt(0)
	v_mfma_f32_16x16x32_bf16 v[126:129], v[142:145], v[196:199], v[126:129]
	v_mfma_f32_16x16x32_bf16 v[118:121], v[172:175], v[196:199], v[118:121]
	v_mfma_f32_16x16x32_bf16 v[110:113], v[142:145], v[218:221], v[110:113]
	v_mfma_f32_16x16x32_bf16 v[102:105], v[172:175], v[218:221], v[102:105]
	v_mfma_f32_16x16x32_bf16 v[94:97], v[142:145], v[226:229], v[94:97]
	v_mfma_f32_16x16x32_bf16 v[86:89], v[172:175], v[226:229], v[86:89]
	v_mfma_f32_16x16x32_bf16 v[78:81], v[142:145], v[234:237], v[78:81]
	v_mfma_f32_16x16x32_bf16 v[70:73], v[172:175], v[234:237], v[70:73]
	v_mfma_f32_16x16x32_bf16 v[126:129], v[152:155], v[214:217], v[126:129]
	v_mfma_f32_16x16x32_bf16 v[118:121], v[176:179], v[214:217], v[118:121]
	v_mfma_f32_16x16x32_bf16 v[110:113], v[152:155], v[222:225], v[110:113]
	v_mfma_f32_16x16x32_bf16 v[102:105], v[176:179], v[222:225], v[102:105]
	v_mfma_f32_16x16x32_bf16 v[94:97], v[152:155], v[230:233], v[94:97]
	v_mfma_f32_16x16x32_bf16 v[86:89], v[176:179], v[230:233], v[86:89]
	v_mfma_f32_16x16x32_bf16 v[78:81], v[152:155], v[238:241], v[78:81]
	v_mfma_f32_16x16x32_bf16 v[70:73], v[176:179], v[238:241], v[70:73]
	s_setprio 0
	s_setprio 1
	v_mfma_f32_16x16x32_bf16 v[122:125], v[180:183], v[196:199], v[122:125]
	v_mfma_f32_16x16x32_bf16 v[114:117], v[188:191], v[196:199], v[114:117]
	v_mfma_f32_16x16x32_bf16 v[106:109], v[180:183], v[218:221], v[106:109]
	v_mfma_f32_16x16x32_bf16 v[98:101], v[188:191], v[218:221], v[98:101]
	v_mfma_f32_16x16x32_bf16 v[90:93], v[180:183], v[226:229], v[90:93]
	v_mfma_f32_16x16x32_bf16 v[82:85], v[188:191], v[226:229], v[82:85]
	v_mfma_f32_16x16x32_bf16 v[74:77], v[180:183], v[234:237], v[74:77]
	v_mfma_f32_16x16x32_bf16 v[66:69], v[188:191], v[234:237], v[66:69]
	v_mfma_f32_16x16x32_bf16 v[122:125], v[184:187], v[214:217], v[122:125]
	v_mfma_f32_16x16x32_bf16 v[114:117], v[192:195], v[214:217], v[114:117]
	v_mfma_f32_16x16x32_bf16 v[106:109], v[184:187], v[222:225], v[106:109]
	v_mfma_f32_16x16x32_bf16 v[98:101], v[192:195], v[222:225], v[98:101]
	v_mfma_f32_16x16x32_bf16 v[90:93], v[184:187], v[230:233], v[90:93]
	v_mfma_f32_16x16x32_bf16 v[82:85], v[192:195], v[230:233], v[82:85]
	v_mfma_f32_16x16x32_bf16 v[74:77], v[184:187], v[238:241], v[74:77]
	v_mfma_f32_16x16x32_bf16 v[66:69], v[192:195], v[238:241], v[66:69]
	s_setprio 0
	s_barrier
; #define PG8_STAGE(bufoff, gbase, voff) do { _Pragma("unroll") for (int _i = 0; _i < 2; ++_i) \
;         __builtin_amdgcn_global_load_lds((const unsigned*)((const char*)(gbase) + (voff)[_i]), (PG8_LAS unsigned*)(lds + (bufoff) + ldsw + _i * 8192), 16, 0, 0); } while (0)
; #define PG8_LDA(dst, b, h) do { _Pragma("unroll") for (int m = 0; m < 4; ++m) _Pragma("unroll") for (int k = 0; k < 2; ++k) dst[m][k] = *(const PG8_LAS bf16x8*)(lds + PG8_SA(b, h) + aoff + m * 2048 + k * 1024); } while (0)
; #define PG8_LDB(dst, b, h) do { _Pragma("unroll") for (int n = 0; n < 2; ++n) _Pragma("unroll") for (int k = 0; k < 2; ++k) dst[n][k] = *(const PG8_LAS bf16x8*)(lds + PG8_SB(b, h) + boff + n * 2048 + k * 1024); } while (0)
; #define PG8_MMA(ai, bj, At, Bt) do { __builtin_amdgcn_s_setprio(1); _Pragma("unroll") for (int m = 0; m < 4; ++m) _Pragma("unroll") for (int n = 0; n < 2; ++n) _Pragma("unroll") for (int k = 0; k < 2; ++k) \
;         acc[ai][bj][m][n] = __builtin_amdgcn_mfma_f32_16x16x32_bf16(Bt[n][k], At[m][k], acc[ai][bj][m][n], 0, 0, 0); __builtin_amdgcn_s_setprio(0); } while (0)
; #define PG8_WAIT_V(n) asm volatile("s_waitcnt vmcnt(" #n ")" ::: "memory")
; #define PG8_WAIT_L(n) asm volatile("s_waitcnt lgkmcnt(" #n ")" ::: "memory")
; template <class Epi, class Sched, bool ALIGN_EPI = false, bool SP2 = false>
; __device__ __forceinline__ void gemm_phase(PG8_LAS unsigned char* lds, const Gemm g, const Sched& S, const Epi& E) {
;     ...
;         for (int t = 0; t < nt; t += 2) {
;             const bool last = (t == nt - 2);
;             const char* a1 = cA + (size_t)(t + 1) * kstep;
;             const char* a2 = last ? nA : cA + (size_t)(t + 2) * kstep; const char* b2 = last ? nB : cB + (size_t)(t + 2) * kstep;
;             const char* a3 = a2 + kstep; const char* b3 = b2 + kstep;
;             if (last && has_next) S.a_ready(nxt);
;     ...
;             PG8_LDB(B0, 1, 0); PG8_LDB(B1, 1, 1); PG8_SCHED; PG8_LDA(At, 1, 0); PG8_STAGE(PG8_SA(0, 1), a2 + hstep, voffA);
;             PG8_WAIT_V(8); PG8_WAIT_L(0); PG8_BAR; PG8_MMA(0, 0, At, B0); PG8_MMA(0, 1, At, B1); PG8_BAR; PG8_SCHED;
;             PG8_LDA(At, 1, 1); PG8_STAGE(PG8_SB(1, 0), b3, voffB); PG8_STAGE(PG8_SB(1, 1), b3 + hstep, voffB); PG8_STAGE(PG8_SA(1, 0), a3, voffA);
;             PG8_WAIT_V(8); PG8_WAIT_L(0); PG8_BAR; PG8_MMA(1, 0, At, B0); PG8_MMA(1, 1, At, B1); PG8_BAR; PG8_SCHED;
	ds_read_b128 v[196:199], v151 offset:49152
	ds_read_b128 v[214:217], v151 offset:50176
	ds_read_b128 v[218:221], v151 offset:51200
	ds_read_b128 v[222:225], v151 offset:52224
	s_add_u32 s98, s26, 0xfffc0080
	s_addc_u32 s99, s27, -1
	s_add_i32 s26, s51, s2
	s_add_u32 s100, s24, 0x80
	s_addc_u32 s101, s25, 0
	s_mov_b32 m0, s26
	ds_read_b128 v[226:229], v151 offset:53248
	ds_read_b128 v[230:233], v151 offset:54272
	ds_read_b128 v[234:237], v151 offset:55296
	ds_read_b128 v[238:241], v151 offset:56320
	global_load_lds_dwordx4 v0, s[100:101]
	s_add_i32 m0, s26, 0x2000
	s_add_u32 s24, s24, 0x40080
	s_addc_u32 s25, s25, 0
	s_add_i32 s26, s52, s2
	global_load_lds_dwordx4 v130, s[100:101]
	s_mov_b32 m0, s26
	s_nop 0
	global_load_lds_dwordx4 v0, s[24:25]
	s_add_i32 m0, s26, 0x2000
	s_nop 0
	global_load_lds_dwordx4 v130, s[24:25]
	s_mov_b32 m0, s37
	s_nop 0
	global_load_lds_dwordx4 v134, s[98:99]
	s_mov_b32 m0, s38
	s_nop 0
	global_load_lds_dwordx4 v132, s[98:99]
	s_add_i32 s50, s50, 2
	s_add_u32 s22, s22, 0x100
	s_addc_u32 s23, s23, 0
	s_add_u32 s48, s48, 0x100
	s_addc_u32 s49, s49, 0
	s_add_u32 s24, s22, 0xfffc0080
	s_addc_u32 s25, s23, -1
	s_add_i32 s51, 0, 0x10000
	s_cmp_eq_u32 s50, 12
	s_cselect_b32 s27, s17, s25
	s_cselect_b32 s26, s46, s24
	s_cselect_b32 s25, s15, s49
	s_cselect_b32 s24, s47, s48
	s_add_i32 s54, 0, 0x14000
	s_cmp_gt_u32 s50, 13
	s_waitcnt vmcnt(8)
	s_waitcnt lgkmcnt(0)
	s_barrier
	s_setprio 1
	s_waitcnt lgkmcnt(0)
	v_mfma_f32_16x16x32_bf16 v[62:65], v[142:145], v[196:199], v[62:65]
	v_mfma_f32_16x16x32_bf16 v[54:57], v[172:175], v[196:199], v[54:57]
	v_mfma_f32_16x16x32_bf16 v[46:49], v[142:145], v[218:221], v[46:49]
	v_mfma_f32_16x16x32_bf16 v[38:41], v[172:175], v[218:221], v[38:41]
	v_mfma_f32_16x16x32_bf16 v[30:33], v[142:145], v[226:229], v[30:33]
	v_mfma_f32_16x16x32_bf16 v[22:25], v[172:175], v[226:229], v[22:25]
	v_mfma_f32_16x16x32_bf16 v[14:17], v[142:145], v[234:237], v[14:17]
	v_mfma_f32_16x16x32_bf16 v[6:9], v[172:175], v[234:237], v[6:9]
	v_mfma_f32_16x16x32_bf16 v[62:65], v[152:155], v[214:217], v[62:65]
	v_mfma_f32_16x16x32_bf16 v[54:57], v[176:179], v[214:217], v[54:57]
	v_mfma_f32_16x16x32_bf16 v[46:49], v[152:155], v[222:225], v[46:49]
	v_mfma_f32_16x16x32_bf16 v[38:41], v[176:179], v[222:225], v[38:41]
	v_mfma_f32_16x16x32_bf16 v[30:33], v[152:155], v[230:233], v[30:33]
	v_mfma_f32_16x16x32_bf16 v[22:25], v[176:179], v[230:233], v[22:25]
	v_mfma_f32_16x16x32_bf16 v[14:17], v[152:155], v[238:241], v[14:17]
	v_mfma_f32_16x16x32_bf16 v[6:9], v[176:179], v[238:241], v[6:9]
	s_setprio 0
	s_setprio 1
	v_mfma_f32_16x16x32_bf16 v[58:61], v[180:183], v[196:199], v[58:61]
	v_mfma_f32_16x16x32_bf16 v[50:53], v[188:191], v[196:199], v[50:53]
	v_mfma_f32_16x16x32_bf16 v[42:45], v[180:183], v[218:221], v[42:45]
	v_mfma_f32_16x16x32_bf16 v[34:37], v[188:191], v[218:221], v[34:37]
	v_mfma_f32_16x16x32_bf16 v[26:29], v[180:183], v[226:229], v[26:29]
	v_mfma_f32_16x16x32_bf16 v[18:21], v[188:191], v[226:229], v[18:21]
	v_mfma_f32_16x16x32_bf16 v[10:13], v[180:183], v[234:237], v[10:13]
	v_mfma_f32_16x16x32_bf16 v[2:5], v[188:191], v[234:237], v[2:5]
	v_mfma_f32_16x16x32_bf16 v[58:61], v[184:187], v[214:217], v[58:61]
	v_mfma_f32_16x16x32_bf16 v[50:53], v[192:195], v[214:217], v[50:53]
	v_mfma_f32_16x16x32_bf16 v[42:45], v[184:187], v[222:225], v[42:45]
	v_mfma_f32_16x16x32_bf16 v[34:37], v[192:195], v[222:225], v[34:37]
	v_mfma_f32_16x16x32_bf16 v[26:29], v[184:187], v[230:233], v[26:29]
	v_mfma_f32_16x16x32_bf16 v[18:21], v[192:195], v[230:233], v[18:21]
	v_mfma_f32_16x16x32_bf16 v[10:13], v[184:187], v[238:241], v[10:13]
	v_mfma_f32_16x16x32_bf16 v[2:5], v[192:195], v[238:241], v[2:5]
	s_setprio 0
	s_barrier
.LBB0_493:
	ds_read_b128 v[142:145], v146
	ds_read_b128 v[152:155], v146 offset:1024
	ds_read_b128 v[172:175], v146 offset:2048
	ds_read_b128 v[176:179], v146 offset:3072
	ds_read_b128 v[180:183], v147
	ds_read_b128 v[184:187], v147 offset:1024
	ds_read_b128 v[188:191], v147 offset:2048
	ds_read_b128 v[192:195], v147 offset:3072
	s_add_i32 m0, s30, 0xc000
	ds_read_b128 v[196:199], v151
	ds_read_b128 v[214:217], v151 offset:1024
	ds_read_b128 v[218:221], v151 offset:2048
	ds_read_b128 v[222:225], v151 offset:3072
	ds_read_b128 v[226:229], v151 offset:4096
	ds_read_b128 v[230:233], v151 offset:5120
	ds_read_b128 v[234:237], v151 offset:6144
	ds_read_b128 v[238:241], v151 offset:7168
	global_load_lds_dwordx4 v138, s[22:23]
	s_add_i32 m0, s30, 0xe000
	s_nop 0
	global_load_lds_dwordx4 v140, s[22:23]
	s_waitcnt vmcnt(8)
	s_waitcnt lgkmcnt(0)
	s_barrier
; #define PG8_STAGE(bufoff, gbase, voff) do { _Pragma("unroll") for (int _i = 0; _i < 2; ++_i) \
;         __builtin_amdgcn_global_load_lds((const unsigned*)((const char*)(gbase) + (voff)[_i]), (PG8_LAS unsigned*)(lds + (bufoff) + ldsw + _i * 8192), 16, 0, 0); } while (0)
; #define PG8_LDA(dst, b, h) do { _Pragma("unroll") for (int m = 0; m < 4; ++m) _Pragma("unroll") for (int k = 0; k < 2; ++k) dst[m][k] = *(const PG8_LAS bf16x8*)(lds + PG8_SA(b, h) + aoff + m * 2048 + k * 1024); } while (0)
; #define PG8_LDB(dst, b, h) do { _Pragma("unroll") for (int n = 0; n < 2; ++n) _Pragma("unroll") for (int k = 0; k < 2; ++k) dst[n][k] = *(const PG8_LAS bf16x8*)(lds + PG8_SB(b, h) + boff + n * 2048 + k * 1024); } while (0)
; #define PG8_MMA(ai, bj, At, Bt) do { __builtin_amdgcn_s_setprio(1); _Pragma("unroll") for (int m = 0; m < 4; ++m) _Pragma("unroll") for (int n = 0; n < 2; ++n) _Pragma("unroll") for (int k = 0; k < 2; ++k) \
;         acc[ai][bj][m][n] = __builtin_amdgcn_mfma_f32_16x16x32_bf16(Bt[n][k], At[m][k], acc[ai][bj][m][n], 0, 0, 0); __builtin_amdgcn_s_setprio(0); } while (0)
; #define PG8_WAIT_V(n) asm volatile("s_waitcnt vmcnt(" #n ")" ::: "memory")
; #define PG8_WAIT_L(n) asm volatile("s_waitcnt lgkmcnt(" #n ")" ::: "memory")
; #define PG8_BAR __builtin_amdgcn_s_barrier()
; #define PG8_SCHED __builtin_amdgcn_sched_barrier(0)
; template <class Epi, class Sched, bool ALIGN_EPI = false, bool SP2 = false>
; __device__ __forceinline__ void gemm_phase(PG8_LAS unsigned char* lds, const Gemm g, const Sched& S, const Epi& E) {
;     ...
;             PG8_LDB(B0, 0, 0); PG8_LDB(B1, 0, 1); PG8_SCHED; PG8_LDA(At, 0, 0); PG8_STAGE(PG8_SA(1, 1), a1 + hstep, voffA);
;             PG8_WAIT_V(8); PG8_WAIT_L(0); PG8_BAR; PG8_MMA(0, 0, At, B0); PG8_MMA(0, 1, At, B1); PG8_BAR; PG8_SCHED;
;             PG8_LDA(At, 0, 1); PG8_STAGE(PG8_SB(0, 0), b2, voffB); PG8_STAGE(PG8_SB(0, 1), b2 + hstep, voffB); PG8_STAGE(PG8_SA(0, 0), a2, voffA);
;             PG8_WAIT_V(8); PG8_WAIT_L(0); PG8_BAR; PG8_MMA(1, 0, At, B0); PG8_MMA(1, 1, At, B1); PG8_BAR; PG8_SCHED;
;             PG8_LDB(B0, 1, 0); PG8_LDB(B1, 1, 1); PG8_SCHED; PG8_LDA(At, 1, 0); PG8_STAGE(PG8_SA(0, 1), a2 + hstep, voffA);
	s_setprio 1
	s_waitcnt lgkmcnt(0)
	v_mfma_f32_16x16x32_bf16 v[126:129], v[142:145], v[196:199], v[126:129]
	v_mfma_f32_16x16x32_bf16 v[118:121], v[172:175], v[196:199], v[118:121]
	v_mfma_f32_16x16x32_bf16 v[110:113], v[142:145], v[218:221], v[110:113]
	v_mfma_f32_16x16x32_bf16 v[102:105], v[172:175], v[218:221], v[102:105]
	v_mfma_f32_16x16x32_bf16 v[94:97], v[142:145], v[226:229], v[94:97]
	v_mfma_f32_16x16x32_bf16 v[86:89], v[172:175], v[226:229], v[86:89]
	v_mfma_f32_16x16x32_bf16 v[78:81], v[142:145], v[234:237], v[78:81]
	v_mfma_f32_16x16x32_bf16 v[70:73], v[172:175], v[234:237], v[70:73]
	v_mfma_f32_16x16x32_bf16 v[126:129], v[152:155], v[214:217], v[126:129]
	v_mfma_f32_16x16x32_bf16 v[118:121], v[176:179], v[214:217], v[118:121]
	v_mfma_f32_16x16x32_bf16 v[110:113], v[152:155], v[222:225], v[110:113]
	v_mfma_f32_16x16x32_bf16 v[102:105], v[176:179], v[222:225], v[102:105]
	v_mfma_f32_16x16x32_bf16 v[94:97], v[152:155], v[230:233], v[94:97]
	v_mfma_f32_16x16x32_bf16 v[86:89], v[176:179], v[230:233], v[86:89]
	v_mfma_f32_16x16x32_bf16 v[78:81], v[152:155], v[238:241], v[78:81]
	v_mfma_f32_16x16x32_bf16 v[70:73], v[176:179], v[238:241], v[70:73]
	s_setprio 0
	s_setprio 1
	v_mfma_f32_16x16x32_bf16 v[122:125], v[180:183], v[196:199], v[122:125]
	v_mfma_f32_16x16x32_bf16 v[114:117], v[188:191], v[196:199], v[114:117]
	v_mfma_f32_16x16x32_bf16 v[106:109], v[180:183], v[218:221], v[106:109]
	v_mfma_f32_16x16x32_bf16 v[98:101], v[188:191], v[218:221], v[98:101]
	v_mfma_f32_16x16x32_bf16 v[90:93], v[180:183], v[226:229], v[90:93]
	v_mfma_f32_16x16x32_bf16 v[82:85], v[188:191], v[226:229], v[82:85]
	v_mfma_f32_16x16x32_bf16 v[74:77], v[180:183], v[234:237], v[74:77]
	v_mfma_f32_16x16x32_bf16 v[66:69], v[188:191], v[234:237], v[66:69]
	v_mfma_f32_16x16x32_bf16 v[122:125], v[184:187], v[214:217], v[122:125]
	v_mfma_f32_16x16x32_bf16 v[114:117], v[192:195], v[214:217], v[114:117]
	v_mfma_f32_16x16x32_bf16 v[106:109], v[184:187], v[222:225], v[106:109]
	v_mfma_f32_16x16x32_bf16 v[98:101], v[192:195], v[222:225], v[98:101]
	v_mfma_f32_16x16x32_bf16 v[90:93], v[184:187], v[230:233], v[90:93]
	v_mfma_f32_16x16x32_bf16 v[82:85], v[192:195], v[230:233], v[82:85]
	v_mfma_f32_16x16x32_bf16 v[74:77], v[184:187], v[238:241], v[74:77]
	v_mfma_f32_16x16x32_bf16 v[66:69], v[192:195], v[238:241], v[66:69]
	s_setprio 0
	s_barrier
	ds_read_b128 v[196:199], v151 offset:16384
	ds_read_b128 v[214:217], v151 offset:17408
	ds_read_b128 v[218:221], v151 offset:18432
	ds_read_b128 v[222:225], v151 offset:19456
	s_add_i32 s51, s51, s2
	s_mov_b32 m0, s51
	ds_read_b128 v[226:229], v151 offset:20480
	ds_read_b128 v[230:233], v151 offset:21504
	ds_read_b128 v[234:237], v151 offset:22528
	ds_read_b128 v[238:241], v151 offset:23552
	global_load_lds_dwordx4 v0, s[24:25]
	s_add_i32 m0, s51, 0x2000
	s_add_u32 s52, s24, 0x40000
	s_addc_u32 s53, s25, 0
	s_add_i32 s51, s54, s2
	global_load_lds_dwordx4 v130, s[24:25]
	s_mov_b32 m0, s51
	s_nop 0
	global_load_lds_dwordx4 v0, s[52:53]
	s_add_i32 m0, s51, 0x2000
	s_nop 0
	global_load_lds_dwordx4 v130, s[52:53]
	s_mov_b32 m0, s30
	s_nop 0
	global_load_lds_dwordx4 v134, s[26:27]
	s_mov_b32 m0, s31
	s_nop 0
	global_load_lds_dwordx4 v132, s[26:27]
	s_waitcnt vmcnt(8)
	s_waitcnt lgkmcnt(0)
	s_barrier
	s_setprio 1
	s_waitcnt lgkmcnt(0)
	v_mfma_f32_16x16x32_bf16 v[62:65], v[142:145], v[196:199], v[62:65]
	v_mfma_f32_16x16x32_bf16 v[54:57], v[172:175], v[196:199], v[54:57]
	v_mfma_f32_16x16x32_bf16 v[46:49], v[142:145], v[218:221], v[46:49]
	v_mfma_f32_16x16x32_bf16 v[38:41], v[172:175], v[218:221], v[38:41]
	v_mfma_f32_16x16x32_bf16 v[30:33], v[142:145], v[226:229], v[30:33]
	v_mfma_f32_16x16x32_bf16 v[22:25], v[172:175], v[226:229], v[22:25]
	v_mfma_f32_16x16x32_bf16 v[14:17], v[142:145], v[234:237], v[14:17]
	v_mfma_f32_16x16x32_bf16 v[6:9], v[172:175], v[234:237], v[6:9]
	v_mfma_f32_16x16x32_bf16 v[62:65], v[152:155], v[214:217], v[62:65]
	v_mfma_f32_16x16x32_bf16 v[54:57], v[176:179], v[214:217], v[54:57]
	v_mfma_f32_16x16x32_bf16 v[46:49], v[152:155], v[222:225], v[46:49]
	v_mfma_f32_16x16x32_bf16 v[38:41], v[176:179], v[222:225], v[38:41]
	v_mfma_f32_16x16x32_bf16 v[30:33], v[152:155], v[230:233], v[30:33]
	v_mfma_f32_16x16x32_bf16 v[22:25], v[176:179], v[230:233], v[22:25]
	v_mfma_f32_16x16x32_bf16 v[14:17], v[152:155], v[238:241], v[14:17]
	v_mfma_f32_16x16x32_bf16 v[6:9], v[176:179], v[238:241], v[6:9]
	s_setprio 0
	s_setprio 1
	v_mfma_f32_16x16x32_bf16 v[58:61], v[180:183], v[196:199], v[58:61]
	v_mfma_f32_16x16x32_bf16 v[50:53], v[188:191], v[196:199], v[50:53]
	v_mfma_f32_16x16x32_bf16 v[42:45], v[180:183], v[218:221], v[42:45]
	v_mfma_f32_16x16x32_bf16 v[34:37], v[188:191], v[218:221], v[34:37]
	v_mfma_f32_16x16x32_bf16 v[26:29], v[180:183], v[226:229], v[26:29]
	v_mfma_f32_16x16x32_bf16 v[18:21], v[188:191], v[226:229], v[18:21]
	v_mfma_f32_16x16x32_bf16 v[10:13], v[180:183], v[234:237], v[10:13]
	v_mfma_f32_16x16x32_bf16 v[2:5], v[188:191], v[234:237], v[2:5]
	v_mfma_f32_16x16x32_bf16 v[58:61], v[184:187], v[214:217], v[58:61]
	v_mfma_f32_16x16x32_bf16 v[50:53], v[192:195], v[214:217], v[50:53]
	v_mfma_f32_16x16x32_bf16 v[42:45], v[184:187], v[222:225], v[42:45]
	v_mfma_f32_16x16x32_bf16 v[34:37], v[192:195], v[222:225], v[34:37]
	v_mfma_f32_16x16x32_bf16 v[26:29], v[184:187], v[230:233], v[26:29]
	v_mfma_f32_16x16x32_bf16 v[18:21], v[192:195], v[230:233], v[18:21]
	v_mfma_f32_16x16x32_bf16 v[10:13], v[184:187], v[238:241], v[10:13]
	v_mfma_f32_16x16x32_bf16 v[2:5], v[192:195], v[238:241], v[2:5]
	s_setprio 0
	s_barrier
; #define PG8_STAGE(bufoff, gbase, voff) do { _Pragma("unroll") for (int _i = 0; _i < 2; ++_i) \
;         __builtin_amdgcn_global_load_lds((const unsigned*)((const char*)(gbase) + (voff)[_i]), (PG8_LAS unsigned*)(lds + (bufoff) + ldsw + _i * 8192), 16, 0, 0); } while (0)
; #define PG8_LDA(dst, b, h) do { _Pragma("unroll") for (int m = 0; m < 4; ++m) _Pragma("unroll") for (int k = 0; k < 2; ++k) dst[m][k] = *(const PG8_LAS bf16x8*)(lds + PG8_SA(b, h) + aoff + m * 2048 + k * 1024); } while (0)
; #define PG8_LDB(dst, b, h) do { _Pragma("unroll") for (int n = 0; n < 2; ++n) _Pragma("unroll") for (int k = 0; k < 2; ++k) dst[n][k] = *(const PG8_LAS bf16x8*)(lds + PG8_SB(b, h) + boff + n * 2048 + k * 1024); } while (0)
; #define PG8_MMA(ai, bj, At, Bt) do { __builtin_amdgcn_s_setprio(1); _Pragma("unroll") for (int m = 0; m < 4; ++m) _Pragma("unroll") for (int n = 0; n < 2; ++n) _Pragma("unroll") for (int k = 0; k < 2; ++k) \
;         acc[ai][bj][m][n] = __builtin_amdgcn_mfma_f32_16x16x32_bf16(Bt[n][k], At[m][k], acc[ai][bj][m][n], 0, 0, 0); __builtin_amdgcn_s_setprio(0); } while (0)
; #define PG8_WAIT_V(n) asm volatile("s_waitcnt vmcnt(" #n ")" ::: "memory")
; #define PG8_WAIT_L(n) asm volatile("s_waitcnt lgkmcnt(" #n ")" ::: "memory")
; #define PG8_BAR __builtin_amdgcn_s_barrier()
; #define PG8_SCHED __builtin_amdgcn_sched_barrier(0)
; template <class Epi, class Sched, bool ALIGN_EPI = false, bool SP2 = false>
; __device__ __forceinline__ void gemm_phase(PG8_LAS unsigned char* lds, const Gemm g, const Sched& S, const Epi& E) {
;     ...
;             PG8_LDA(At, 0, 1); PG8_STAGE(PG8_SB(0, 0), b2, voffB); PG8_STAGE(PG8_SB(0, 1), b2 + hstep, voffB); PG8_STAGE(PG8_SA(0, 0), a2, voffA);
;             PG8_WAIT_V(8); PG8_WAIT_L(0); PG8_BAR; PG8_MMA(1, 0, At, B0); PG8_MMA(1, 1, At, B1); PG8_BAR; PG8_SCHED;
;             PG8_LDB(B0, 1, 0); PG8_LDB(B1, 1, 1); PG8_SCHED; PG8_LDA(At, 1, 0); PG8_STAGE(PG8_SA(0, 1), a2 + hstep, voffA);
;             PG8_WAIT_V(8); PG8_WAIT_L(0); PG8_BAR; PG8_MMA(0, 0, At, B0); PG8_MMA(0, 1, At, B1); PG8_BAR; PG8_SCHED;
;             PG8_LDA(At, 1, 1); PG8_STAGE(PG8_SB(1, 0), b3, voffB); PG8_STAGE(PG8_SB(1, 1), b3 + hstep, voffB); PG8_STAGE(PG8_SA(1, 0), a3, voffA);
;             PG8_WAIT_V(8); PG8_WAIT_L(0); PG8_BAR; PG8_MMA(1, 0, At, B0); PG8_MMA(1, 1, At, B1); PG8_BAR; PG8_SCHED;
	ds_read_b128 v[142:145], v156
	ds_read_b128 v[152:155], v156 offset:1024
	ds_read_b128 v[172:175], v156 offset:2048
	ds_read_b128 v[176:179], v156 offset:3072
	ds_read_b128 v[180:183], v157
	ds_read_b128 v[184:187], v157 offset:1024
	ds_read_b128 v[188:191], v157 offset:2048
	ds_read_b128 v[192:195], v157 offset:3072
	s_add_i32 s51, 0, 0x18000
	s_add_i32 s52, 0, 0x1c000
	s_add_u32 s26, s26, 0x40000
	s_addc_u32 s27, s27, 0
	s_mov_b32 m0, s34
	ds_read_b128 v[196:199], v151 offset:32768
	ds_read_b128 v[214:217], v151 offset:33792
	ds_read_b128 v[218:221], v151 offset:34816
	ds_read_b128 v[222:225], v151 offset:35840
	ds_read_b128 v[226:229], v151 offset:36864
	ds_read_b128 v[230:233], v151 offset:37888
	ds_read_b128 v[234:237], v151 offset:38912
	ds_read_b128 v[238:241], v151 offset:39936
	global_load_lds_dwordx4 v134, s[26:27]
	s_mov_b32 m0, s35
	s_nop 0
	global_load_lds_dwordx4 v132, s[26:27]
	s_waitcnt vmcnt(8)
	s_waitcnt lgkmcnt(0)
	s_barrier
	s_setprio 1
	s_waitcnt lgkmcnt(0)
	v_mfma_f32_16x16x32_bf16 v[126:129], v[142:145], v[196:199], v[126:129]
	v_mfma_f32_16x16x32_bf16 v[118:121], v[172:175], v[196:199], v[118:121]
	v_mfma_f32_16x16x32_bf16 v[110:113], v[142:145], v[218:221], v[110:113]
	v_mfma_f32_16x16x32_bf16 v[102:105], v[172:175], v[218:221], v[102:105]
	v_mfma_f32_16x16x32_bf16 v[94:97], v[142:145], v[226:229], v[94:97]
	v_mfma_f32_16x16x32_bf16 v[86:89], v[172:175], v[226:229], v[86:89]
	v_mfma_f32_16x16x32_bf16 v[78:81], v[142:145], v[234:237], v[78:81]
	v_mfma_f32_16x16x32_bf16 v[70:73], v[172:175], v[234:237], v[70:73]
	v_mfma_f32_16x16x32_bf16 v[126:129], v[152:155], v[214:217], v[126:129]
	v_mfma_f32_16x16x32_bf16 v[118:121], v[176:179], v[214:217], v[118:121]
	v_mfma_f32_16x16x32_bf16 v[110:113], v[152:155], v[222:225], v[110:113]
	v_mfma_f32_16x16x32_bf16 v[102:105], v[176:179], v[222:225], v[102:105]
	v_mfma_f32_16x16x32_bf16 v[94:97], v[152:155], v[230:233], v[94:97]
	v_mfma_f32_16x16x32_bf16 v[86:89], v[176:179], v[230:233], v[86:89]
	v_mfma_f32_16x16x32_bf16 v[78:81], v[152:155], v[238:241], v[78:81]
	v_mfma_f32_16x16x32_bf16 v[70:73], v[176:179], v[238:241], v[70:73]
	s_setprio 0
	s_setprio 1
	v_mfma_f32_16x16x32_bf16 v[122:125], v[180:183], v[196:199], v[122:125]
	v_mfma_f32_16x16x32_bf16 v[114:117], v[188:191], v[196:199], v[114:117]
	v_mfma_f32_16x16x32_bf16 v[106:109], v[180:183], v[218:221], v[106:109]
	v_mfma_f32_16x16x32_bf16 v[98:101], v[188:191], v[218:221], v[98:101]
	v_mfma_f32_16x16x32_bf16 v[90:93], v[180:183], v[226:229], v[90:93]
	v_mfma_f32_16x16x32_bf16 v[82:85], v[188:191], v[226:229], v[82:85]
	v_mfma_f32_16x16x32_bf16 v[74:77], v[180:183], v[234:237], v[74:77]
	v_mfma_f32_16x16x32_bf16 v[66:69], v[188:191], v[234:237], v[66:69]
	v_mfma_f32_16x16x32_bf16 v[122:125], v[184:187], v[214:217], v[122:125]
	v_mfma_f32_16x16x32_bf16 v[114:117], v[192:195], v[214:217], v[114:117]
	v_mfma_f32_16x16x32_bf16 v[106:109], v[184:187], v[222:225], v[106:109]
	v_mfma_f32_16x16x32_bf16 v[98:101], v[192:195], v[222:225], v[98:101]
	v_mfma_f32_16x16x32_bf16 v[90:93], v[184:187], v[230:233], v[90:93]
	v_mfma_f32_16x16x32_bf16 v[82:85], v[192:195], v[230:233], v[82:85]
	v_mfma_f32_16x16x32_bf16 v[74:77], v[184:187], v[238:241], v[74:77]
	v_mfma_f32_16x16x32_bf16 v[66:69], v[192:195], v[238:241], v[66:69]
	s_setprio 0
	s_barrier
	ds_read_b128 v[196:199], v151 offset:49152
	ds_read_b128 v[214:217], v151 offset:50176
	ds_read_b128 v[218:221], v151 offset:51200
	ds_read_b128 v[222:225], v151 offset:52224
	s_add_u32 s98, s26, 0xfffc0080
	s_addc_u32 s99, s27, -1
	s_add_i32 s26, s51, s2
	s_add_u32 s100, s24, 0x80
	s_addc_u32 s101, s25, 0
	s_mov_b32 m0, s26
	ds_read_b128 v[226:229], v151 offset:53248
	ds_read_b128 v[230:233], v151 offset:54272
	ds_read_b128 v[234:237], v151 offset:55296
	ds_read_b128 v[238:241], v151 offset:56320
	global_load_lds_dwordx4 v0, s[100:101]
	s_add_i32 m0, s26, 0x2000
	s_add_u32 s24, s24, 0x40080
	s_addc_u32 s25, s25, 0
	s_add_i32 s26, s52, s2
	global_load_lds_dwordx4 v130, s[100:101]
	s_mov_b32 m0, s26
	s_nop 0
	global_load_lds_dwordx4 v0, s[24:25]
	s_add_i32 m0, s26, 0x2000
	s_nop 0
	global_load_lds_dwordx4 v130, s[24:25]
	s_mov_b32 m0, s37
	s_nop 0
	global_load_lds_dwordx4 v134, s[98:99]
	s_mov_b32 m0, s38
	s_nop 0
	global_load_lds_dwordx4 v132, s[98:99]
	s_add_i32 s50, s50, 2
	s_add_u32 s22, s22, 0x100
	s_addc_u32 s23, s23, 0
	s_add_u32 s48, s48, 0x100
	s_addc_u32 s49, s49, 0
	s_add_u32 s24, s22, 0xfffc0080
	s_addc_u32 s25, s23, -1
	s_add_i32 s51, 0, 0x10000
	s_cmp_eq_u32 s50, 12
	s_cselect_b32 s27, s17, s25
	s_cselect_b32 s26, s46, s24
	s_cselect_b32 s25, s15, s49
	s_cselect_b32 s24, s47, s48
	s_add_i32 s54, 0, 0x14000
	s_cmp_gt_u32 s50, 13
	s_waitcnt vmcnt(8)
	s_waitcnt lgkmcnt(0)
	s_barrier
; #define PG8_STAGE(bufoff, gbase, voff) do { _Pragma("unroll") for (int _i = 0; _i < 2; ++_i) \
;         __builtin_amdgcn_global_load_lds((const unsigned*)((const char*)(gbase) + (voff)[_i]), (PG8_LAS unsigned*)(lds + (bufoff) + ldsw + _i * 8192), 16, 0, 0); } while (0)
; #define PG8_LDA(dst, b, h) do { _Pragma("unroll") for (int m = 0; m < 4; ++m) _Pragma("unroll") for (int k = 0; k < 2; ++k) dst[m][k] = *(const PG8_LAS bf16x8*)(lds + PG8_SA(b, h) + aoff + m * 2048 + k * 1024); } while (0)
; #define PG8_MMA(ai, bj, At, Bt) do { __builtin_amdgcn_s_setprio(1); _Pragma("unroll") for (int m = 0; m < 4; ++m) _Pragma("unroll") for (int n = 0; n < 2; ++n) _Pragma("unroll") for (int k = 0; k < 2; ++k) \
;         acc[ai][bj][m][n] = __builtin_amdgcn_mfma_f32_16x16x32_bf16(Bt[n][k], At[m][k], acc[ai][bj][m][n], 0, 0, 0); __builtin_amdgcn_s_setprio(0); } while (0)
; #define PG8_WAIT_V(n) asm volatile("s_waitcnt vmcnt(" #n ")" ::: "memory")
; #define PG8_WAIT_L(n) asm volatile("s_waitcnt lgkmcnt(" #n ")" ::: "memory")
; #define PG8_BAR __builtin_amdgcn_s_barrier()
; #define PG8_SCHED __builtin_amdgcn_sched_barrier(0)
; template <class Epi, class Sched, bool ALIGN_EPI = false, bool SP2 = false>
; __device__ __forceinline__ void gemm_phase(PG8_LAS unsigned char* lds, const Gemm g, const Sched& S, const Epi& E) {
;     ...
;             PG8_WAIT_V(8); PG8_WAIT_L(0); PG8_BAR; PG8_MMA(0, 0, At, B0); PG8_MMA(0, 1, At, B1); PG8_BAR; PG8_SCHED;
;             PG8_LDA(At, 1, 1); PG8_STAGE(PG8_SB(1, 0), b3, voffB); PG8_STAGE(PG8_SB(1, 1), b3 + hstep, voffB); PG8_STAGE(PG8_SA(1, 0), a3, voffA);
;             PG8_WAIT_V(8); PG8_WAIT_L(0); PG8_BAR; PG8_MMA(1, 0, At, B0); PG8_MMA(1, 1, At, B1); PG8_BAR; PG8_SCHED;
;     __device__ __forceinline__ void operator()(const f32x4 (&acc)[2][2][4][2], const Unit& u, int wr, int wc, int fr, int fq) const {
;         const int row0 = u.pm * BM + wr * 64 + fr, col0 = u.pn * HALF + wc * 32 + 8 * fq;
; #pragma unroll
;         for (int ai = 0; ai < 2; ++ai)
; #pragma unroll
;             for (int m = 0; m < 4; ++m) {
;                 const int row = row0 + ai * HALF + m * 16; const float rs = row_rstd(rsp, row, fq);
;                 const float nrs = -LOG2E * rs, rs2 = rs * rs;
;                 const f32x4 g0 = acc[ai][0][m][0], g1 = acc[ai][0][m][1], u0 = acc[ai][1][m][0], u1 = acc[ai][1][m][1];
	s_setprio 1
	s_waitcnt lgkmcnt(0)
	v_mfma_f32_16x16x32_bf16 v[62:65], v[142:145], v[196:199], v[62:65]
	v_mfma_f32_16x16x32_bf16 v[54:57], v[172:175], v[196:199], v[54:57]
	v_mfma_f32_16x16x32_bf16 v[46:49], v[142:145], v[218:221], v[46:49]
	v_mfma_f32_16x16x32_bf16 v[38:41], v[172:175], v[218:221], v[38:41]
	v_mfma_f32_16x16x32_bf16 v[30:33], v[142:145], v[226:229], v[30:33]
	v_mfma_f32_16x16x32_bf16 v[22:25], v[172:175], v[226:229], v[22:25]
	v_mfma_f32_16x16x32_bf16 v[14:17], v[142:145], v[234:237], v[14:17]
	v_mfma_f32_16x16x32_bf16 v[6:9], v[172:175], v[234:237], v[6:9]
	v_mfma_f32_16x16x32_bf16 v[62:65], v[152:155], v[214:217], v[62:65]
	v_mfma_f32_16x16x32_bf16 v[54:57], v[176:179], v[214:217], v[54:57]
	v_mfma_f32_16x16x32_bf16 v[46:49], v[152:155], v[222:225], v[46:49]
	v_mfma_f32_16x16x32_bf16 v[38:41], v[176:179], v[222:225], v[38:41]
	v_mfma_f32_16x16x32_bf16 v[30:33], v[152:155], v[230:233], v[30:33]
	v_mfma_f32_16x16x32_bf16 v[22:25], v[176:179], v[230:233], v[22:25]
	v_mfma_f32_16x16x32_bf16 v[14:17], v[152:155], v[238:241], v[14:17]
	v_mfma_f32_16x16x32_bf16 v[6:9], v[176:179], v[238:241], v[6:9]
	s_setprio 0
	s_setprio 1
	v_mfma_f32_16x16x32_bf16 v[58:61], v[180:183], v[196:199], v[58:61]
	v_mfma_f32_16x16x32_bf16 v[50:53], v[188:191], v[196:199], v[50:53]
	v_mfma_f32_16x16x32_bf16 v[42:45], v[180:183], v[218:221], v[42:45]
	v_mfma_f32_16x16x32_bf16 v[34:37], v[188:191], v[218:221], v[34:37]
	v_mfma_f32_16x16x32_bf16 v[26:29], v[180:183], v[226:229], v[26:29]
	v_mfma_f32_16x16x32_bf16 v[18:21], v[188:191], v[226:229], v[18:21]
	v_mfma_f32_16x16x32_bf16 v[10:13], v[180:183], v[234:237], v[10:13]
	v_mfma_f32_16x16x32_bf16 v[2:5], v[188:191], v[234:237], v[2:5]
	v_mfma_f32_16x16x32_bf16 v[58:61], v[184:187], v[214:217], v[58:61]
	v_mfma_f32_16x16x32_bf16 v[50:53], v[192:195], v[214:217], v[50:53]
	v_mfma_f32_16x16x32_bf16 v[42:45], v[184:187], v[222:225], v[42:45]
	v_mfma_f32_16x16x32_bf16 v[34:37], v[192:195], v[222:225], v[34:37]
	v_mfma_f32_16x16x32_bf16 v[26:29], v[184:187], v[230:233], v[26:29]
	v_mfma_f32_16x16x32_bf16 v[18:21], v[192:195], v[230:233], v[18:21]
	v_mfma_f32_16x16x32_bf16 v[10:13], v[184:187], v[238:241], v[10:13]
	v_mfma_f32_16x16x32_bf16 v[2:5], v[192:195], v[238:241], v[2:5]
	s_setprio 0
	s_barrier
	s_cbranch_scc0 .LBB0_493
	v_lshl_add_u32 v142, s45, 8, v148
	v_mov_b32_e32 v143, 0
	s_mov_b32 s26, 0x2000
	s_mov_b32 s27, 0
	v_lshlrev_b64 v[146:147], 6, v[142:143]
	v_lshl_add_u64 v[146:147], v[136:137], 0, v[146:147]
	v_lshl_add_u64 v[156:157], v[146:147], 0, s[26:27]
	global_load_dwordx4 v[172:175], v[146:147], off
	global_load_dwordx4 v[176:179], v[146:147], off offset:1024
	global_load_dwordx4 v[180:183], v[146:147], off offset:2048
	global_load_dwordx4 v[184:187], v[146:147], off offset:3072
	global_load_dwordx4 v[188:191], v[156:157], off
	global_load_dwordx4 v[192:195], v[156:157], off offset:1024
	global_load_dwordx4 v[196:199], v[156:157], off offset:2048
	global_load_dwordx4 v[214:217], v[156:157], off offset:3072
	v_xor_b32_e32 v152, 16, v201
	v_xor_b32_e32 v153, 32, v201
	v_lshlrev_b32_e32 v152, 2, v152
	v_lshlrev_b32_e32 v153, 2, v153
	v_lshl_or_b32 v144, s44, 7, v150
	v_mov_b32_e32 v145, 0
	v_mov_b32_e32 v238, s0
	v_mov_b32_e32 v239, s1
	v_mad_i64_i32 v[236:237], s[22:23], v142, s93, v[238:239]
	v_lshlrev_b64 v[240:241], 1, v[144:145]
	v_mov_b32_e32 v234, 1.0
	v_mov_b32_e32 v235, 1.0
	v_lshl_add_u64 v[236:237], v[236:237], 0, v[240:241]
	s_mov_b32 s26, 0x16000
	s_mov_b32 s24, 0x6e000
	s_mov_b32 s25, 0
	s_and_b64 vcc, exec, s[12:13]
	s_cbranch_vccz .LBB0_496
	s_barrier
